# pass-0 GLA unit: the 48 prep loads (gate logs, k, V image) use scalar bases + lane offset; 31 v_add_co/v_addc_co pairs and their nops replaced by SALU adds
# baseline (speedup 1.0000x reference)
; template <int PASS>
; __device__ __forceinline__ void gla_unit(LAS unsigned char* lds, int ch, int h, const bf16* PROJ, const bf16* GT, bf16* STG, float* DECG, bf16* OMIX, const float* gla_norm) {
;     ...
;         const bf16* gp = GT + ((size_t)d * MALL + m0 + 16 * qt) * 256 + h * 64 + kk;
;         const bf16* qp = PROJ + (m0 + 16 * qt) * LDP + PQ + h * 64 + kk; const bf16* kp = PROJ + (m0 + 16 * qt) * LDP + PK + h * 64 + kk;
;         float c[16], kv[16], qv[16];
; #pragma unroll
;         for (int jj = 0; jj < 16; ++jj) { c[jj] = bf1(gp[(size_t)jj * 256]); kv[jj] = bf1(kp[(size_t)jj * LDP]); if (PASS == 1) qv[jj] = bf1(qp[(size_t)jj * LDP]); }
;         if (d == 0) {
; #pragma unroll
;             for (int jj = 1; jj < 16; ++jj) c[jj] += c[jj - 1];
.LBB0_604:
	s_and_b64 vcc, exec, s[0:1]
	s_cbranch_vccz .LBB0_561
	s_ashr_i32 s58, s88, 2
	v_mov_b32_e32 v48, v0
	s_ashr_i32 s59, s58, 31
	v_ashrrev_i32_e32 v36, 6, v48
	v_ashrrev_i32_e32 v49, 8, v48
	s_lshl_b64 s[6:7], s[58:59], 6
	v_and_b32_e32 v51, 3, v36
	v_mul_hi_i32_i24_e32 v5, 0x4400, v49
	v_mul_i32_i24_e32 v4, 0x4400, v49
	v_lshl_add_u64 v[4:5], v[4:5], 0, s[6:7]
	v_lshlrev_b32_e32 v6, 4, v51
	v_or_b32_e32 v4, v4, v6
	v_or_b32_e32 v8, s6, v6
	v_mov_b64_e32 v[6:7], s[54:55]
	v_and_b32_e32 v50, 63, v48
	v_mad_u64_u32 v[6:7], s[0:1], v8, s73, v[6:7]
	v_lshlrev_b32_e32 v2, 1, v50
	v_lshlrev_b32_e32 v158, 1, v50
	v_mad_i32_i24 v7, s7, v1, v7
	v_lshl_add_u64 v[6:7], v[6:7], 0, v[2:3]
	s_nop 0
	v_readfirstlane_b32 s90, v6
	v_readfirstlane_b32 s91, v7
	s_nop 4
	v_lshlrev_b64 v[4:5], 9, v[4:5]
	v_lshl_add_u64 v[4:5], s[44:45], 0, v[4:5]
	v_lshl_add_u64 v[4:5], v[4:5], 0, v[2:3]
	s_nop 0
	v_readfirstlane_b32 s12, v4
	v_readfirstlane_b32 s13, v5
	s_nop 4
	global_load_ushort v2, v158, s[12:13]
	global_load_ushort v37, v158, s[12:13] offset:512
	global_load_ushort v38, v158, s[12:13] offset:1024
	global_load_ushort v39, v158, s[12:13] offset:1536
	global_load_ushort v40, v158, s[12:13] offset:2048
	global_load_ushort v41, v158, s[12:13] offset:2560
	global_load_ushort v42, v158, s[12:13] offset:3072
	global_load_ushort v43, v158, s[12:13] offset:3584
	s_movk_i32 s0, 0x100
	v_readfirstlane_b32 s26, v36
	v_cmp_gt_u32_e64 s[4:5], s0, v48
	s_waitcnt vmcnt(5)
	v_lshlrev_b32_e32 v36, 16, v38
	s_add_u32 s8, s12, s61
	s_addc_u32 s9, s13, 0
	s_waitcnt vmcnt(3)
	v_lshlrev_b32_e32 v38, 16, v40
	s_add_u32 s98, s90, s72
	s_addc_u32 s99, s91, 0
	global_load_ushort v52, v158, s[98:99] offset:1536
	global_load_ushort v44, v158, s[8:9]
	global_load_ushort v45, v158, s[8:9] offset:512
	global_load_ushort v46, v158, s[8:9] offset:1024
	global_load_ushort v47, v158, s[8:9] offset:1536
	global_load_ushort v68, v158, s[8:9] offset:2048
	global_load_ushort v69, v158, s[8:9] offset:2560
	global_load_ushort v70, v158, s[8:9] offset:3072
	s_waitcnt vmcnt(9)
	v_lshlrev_b32_e32 v40, 16, v42
	s_waitcnt vmcnt(6)
	v_lshlrev_b32_e32 v42, 16, v44
	s_waitcnt vmcnt(4)
	v_lshlrev_b32_e32 v44, 16, v46
	s_waitcnt vmcnt(2)
	v_lshlrev_b32_e32 v46, 16, v68
	s_add_u32 s100, s90, s74
	s_addc_u32 s101, s91, 0
	global_load_ushort v59, v158, s[100:101] offset:3200
	s_add_u32 s98, s90, s75
	s_addc_u32 s99, s91, 0
	global_load_ushort v57, v158, s[98:99] offset:768
	s_add_u32 s100, s90, s80
	s_addc_u32 s101, s91, 0
	global_load_ushort v58, v158, s[100:101] offset:2432
	s_add_u32 s98, s90, s81
	s_addc_u32 s99, s91, 0
	global_load_ushort v53, v158, s[98:99]
	s_add_u32 s100, s90, s82
	s_addc_u32 s101, s91, 0
	global_load_ushort v55, v158, s[100:101] offset:1664
	s_add_u32 s98, s90, s83
	s_addc_u32 s99, s91, 0
	global_load_ushort v54, v158, s[98:99] offset:3328
	s_add_u32 s100, s90, 0x15000
	s_addc_u32 s101, s91, 0
	global_load_ushort v56, v158, s[100:101] offset:896
	global_load_ushort v4, v158, s[8:9] offset:3584
	global_load_ushort v65, v158, s[90:91] offset:512
	s_add_u32 s98, s90, s61
	s_addc_u32 s99, s91, 0
	global_load_ushort v67, v158, s[98:99] offset:2176
	s_add_u32 s100, s90, s62
	s_addc_u32 s101, s91, 0
	global_load_ushort v63, v158, s[100:101] offset:3840
	s_add_u32 s98, s90, s66
	s_addc_u32 s99, s91, 0
	global_load_ushort v66, v158, s[98:99] offset:1408
	s_add_u32 s100, s90, s67
	s_addc_u32 s101, s91, 0
	global_load_ushort v61, v158, s[100:101] offset:3072
	s_add_u32 s98, s90, s68
	s_addc_u32 s99, s91, 0
	global_load_ushort v64, v158, s[98:99] offset:640
	s_add_u32 s100, s90, s69
	s_addc_u32 s101, s91, 0
	global_load_ushort v60, v158, s[100:101] offset:2304
	s_add_u32 s98, s90, s70
	s_addc_u32 s99, s91, 0
	global_load_ushort v62, v158, s[98:99] offset:3968
	v_lshlrev_b32_e32 v7, 16, v37
	v_lshlrev_b32_e32 v6, 16, v2
	v_lshlrev_b32_e32 v37, 16, v39
	v_lshlrev_b32_e32 v39, 16, v41
	v_lshlrev_b32_e32 v41, 16, v43
	v_lshlrev_b32_e32 v43, 16, v45
	v_lshlrev_b32_e32 v45, 16, v47
	s_waitcnt vmcnt(17)
	v_lshlrev_b32_e32 v47, 16, v69
	s_waitcnt vmcnt(16)
	v_lshlrev_b32_e32 v8, 16, v70
	v_cmp_lt_u32_e32 vcc, s84, v48
	s_waitcnt vmcnt(8)
	v_lshlrev_b32_e32 v9, 16, v4
	s_and_saveexec_b64 s[0:1], s[4:5]
	s_xor_b64 s[0:1], exec, s[0:1]
	s_cbranch_execz .LBB0_607
	v_pk_add_f32 v[34:35], v[6:7], v[6:7] op_sel:[1,0] op_sel_hi:[0,1]
	v_pk_add_f32 v[32:33], v[34:35], v[36:37]
	s_nop 0
	v_pk_add_f32 v[30:31], v[32:33], v[36:37] op_sel:[0,1] op_sel_hi:[1,0]
	s_nop 0
	v_pk_add_f32 v[28:29], v[30:31], v[38:39]
	s_nop 0
	v_pk_add_f32 v[26:27], v[28:29], v[38:39] op_sel:[0,1] op_sel_hi:[1,0]
	s_nop 0
	v_pk_add_f32 v[24:25], v[26:27], v[40:41]
	s_nop 0
	v_pk_add_f32 v[22:23], v[24:25], v[40:41] op_sel:[0,1] op_sel_hi:[1,0]
	s_nop 0
	v_pk_add_f32 v[20:21], v[22:23], v[42:43]
	s_nop 0
	v_pk_add_f32 v[18:19], v[20:21], v[42:43] op_sel:[0,1] op_sel_hi:[1,0]
	s_nop 0
	v_pk_add_f32 v[16:17], v[18:19], v[44:45]
	s_nop 0
	v_pk_add_f32 v[14:15], v[16:17], v[44:45] op_sel:[0,1] op_sel_hi:[1,0]
	s_nop 0
	v_pk_add_f32 v[12:13], v[14:15], v[46:47]
	s_nop 0
	v_pk_add_f32 v[10:11], v[12:13], v[46:47] op_sel:[0,1] op_sel_hi:[1,0]
	s_nop 0
	v_pk_add_f32 v[4:5], v[10:11], v[8:9]
	s_nop 0
	v_pk_add_f32 v[8:9], v[4:5], v[8:9] op_sel:[0,1] op_sel_hi:[1,0]
	s_nop 0
	v_mov_b32_e32 v9, v8

; #define LAS __attribute__((address_space(3)))
; template <int PASS>
; __device__ __forceinline__ void gla_unit(LAS unsigned char* lds, int ch, int h, const bf16* PROJ, const bf16* GT, bf16* STG, float* DECG, bf16* OMIX, const float* gla_norm) {
;     ...
;         OFFS[(d * 4 + qt) * 64 + kk] = d ? c[0] : c[15];
;         { const int vcol = tid & 127, q4 = tid >> 7; const bf16* vp = PROJ + (m0 + 16 * q4) * LDP + PV + h * 128 + vcol; unsigned vv[16];
; #pragma unroll
;           for (int jj = 0; jj < 16; ++jj) vv[jj] = vp[(size_t)jj * LDP];
; #pragma unroll
;           for (int jj = 0; jj < 16; ++jj) asm volatile("" : "+v"(vv[jj]));
;           v4u w0, w1; w0.x = vv[0] | (vv[1] << 16); w0.y = vv[2] | (vv[3] << 16); w0.z = vv[4] | (vv[5] << 16); w0.w = vv[6] | (vv[7] << 16);
;           w1.x = vv[8] | (vv[9] << 16); w1.y = vv[10] | (vv[11] << 16); w1.z = vv[12] | (vv[13] << 16); w1.w = vv[14] | (vv[15] << 16);
;           *(LAS v4u*)(VT + vcol * RS + q4 * 32) = w0; *(LAS v4u*)(VT + vcol * RS + q4 * 32 + 16) = w1; }
;         __syncthreads();
;         float off = 0.f, tot = 0.f;
; #pragma unroll
;         for (int q2 = 0; q2 < 4; ++q2) { const float t = OFFS[(d * 4 + q2) * 64 + kk]; tot += t; if (d ? (q2 > qt) : (q2 < qt)) off += t; }
.LBB0_609:
	s_or_b64 exec, exec, s[0:1]
	v_ashrrev_i32_e32 v7, 7, v48
	v_lshlrev_b32_e32 v36, 4, v7
	v_ashrrev_i32_e32 v37, 31, v36
	v_lshl_add_u64 v[36:37], s[6:7], 0, v[36:37]
	v_mov_b64_e32 v[38:39], s[56:57]
	v_and_b32_e32 v5, 0x7f, v48
	v_mad_u64_u32 v[38:39], s[0:1], v36, s73, v[38:39]
	v_mad_i32_i24 v39, v37, s73, v39
	v_lshlrev_b32_e32 v2, 1, v5
	v_lshl_add_u64 v[36:37], v[38:39], 0, v[2:3]
	s_nop 0
	v_readfirstlane_b32 s90, v36
	v_readfirstlane_b32 s91, v37
	s_nop 4
	s_mov_b32 s0, 0x15000
	global_load_ushort v2, v158, s[90:91] offset:1024
	s_add_u32 s98, s90, s61
	s_addc_u32 s99, s91, 0
	global_load_ushort v8, v158, s[98:99] offset:2688
	s_add_u32 s100, s90, s65
	s_addc_u32 s101, s91, 0
	global_load_ushort v11, v158, s[100:101] offset:256
	s_add_u32 s98, s90, s66
	s_addc_u32 s99, s91, 0
	global_load_ushort v13, v158, s[98:99] offset:1920
	s_add_u32 s100, s90, s67
	s_addc_u32 s101, s91, 0
	global_load_ushort v15, v158, s[100:101] offset:3584
	s_add_u32 s98, s90, s68
	s_addc_u32 s99, s91, 0
	global_load_ushort v17, v158, s[98:99] offset:1152
	s_add_u32 s100, s90, s69
	s_addc_u32 s101, s91, 0
	global_load_ushort v19, v158, s[100:101] offset:2816
	s_add_u32 s98, s90, s71
	s_addc_u32 s99, s91, 0
	global_load_ushort v21, v158, s[98:99] offset:384
	s_add_u32 s8, s90, s0
	s_addc_u32 s9, s91, 0
	s_mov_b64 s[0:1], 0
	s_add_u32 s100, s90, s72
	s_addc_u32 s101, s91, 0
	global_load_ushort v23, v158, s[100:101] offset:2048
	s_add_u32 s98, s90, s74
	s_addc_u32 s99, s91, 0
	global_load_ushort v25, v158, s[98:99] offset:3712
	s_add_u32 s100, s90, s75
	s_addc_u32 s101, s91, 0
	global_load_ushort v27, v158, s[100:101] offset:1280
	s_add_u32 s98, s90, s80
	s_addc_u32 s99, s91, 0
	global_load_ushort v29, v158, s[98:99] offset:2944
	s_add_u32 s100, s90, s81
	s_addc_u32 s101, s91, 0
	global_load_ushort v31, v158, s[100:101] offset:512
	s_add_u32 s98, s90, s82
	s_addc_u32 s99, s91, 0
	global_load_ushort v33, v158, s[98:99] offset:2176
	s_add_u32 s100, s90, s83
	s_addc_u32 s101, s91, 0
	global_load_ushort v35, v158, s[100:101] offset:3840
	global_load_ushort v37, v158, s[8:9] offset:1408
	v_lshlrev_b32_e32 v46, 10, v49
	v_lshlrev_b32_e32 v39, 8, v51
	v_add_u32_e32 v40, s85, v46
	v_lshlrev_b32_e32 v36, 2, v50
	v_cndmask_b32_e32 v38, v9, v6, vcc
	v_add3_u32 v39, v40, v39, v36
	ds_write_b32 v39, v38
	s_waitcnt vmcnt(15)
	s_waitcnt vmcnt(14)
	s_waitcnt vmcnt(13)
	s_waitcnt vmcnt(12)
	s_waitcnt vmcnt(11)
	s_waitcnt vmcnt(10)
	s_waitcnt vmcnt(9)
	v_lshl_or_b32 v38, v8, 16, v2
	v_mul_u32_u24_e32 v2, 0x90, v5
	v_lshlrev_b32_e32 v5, 5, v7
	s_waitcnt vmcnt(8)
	v_lshl_or_b32 v39, v13, 16, v11
	v_lshl_or_b32 v40, v17, 16, v15
	v_lshl_or_b32 v41, v21, 16, v19
	v_add3_u32 v2, 0, v2, v5
	s_waitcnt vmcnt(7)
	s_waitcnt vmcnt(6)
	s_waitcnt vmcnt(5)
	s_waitcnt vmcnt(4)
	s_waitcnt vmcnt(3)
	s_waitcnt vmcnt(2)
	s_waitcnt vmcnt(1)
	s_waitcnt vmcnt(0)
	v_lshl_or_b32 v42, v25, 16, v23
	v_lshl_or_b32 v43, v29, 16, v27
	v_lshl_or_b32 v44, v33, 16, v31
	v_lshl_or_b32 v45, v37, 16, v35
	ds_write_b128 v2, v[38:41] offset:55296
	ds_write_b128 v2, v[42:45] offset:55312
	v_add_u32_e32 v2, s85, v36
	v_add_u32_e32 v2, v2, v46
	s_waitcnt lgkmcnt(0)
	s_barrier
	ds_read2st64_b32 v[38:39], v2 offset1:1
	v_cmp_eq_u32_e64 s[6:7], 0, v51
	s_and_saveexec_b64 s[8:9], s[4:5]
	s_xor_b64 s[12:13], exec, s[8:9]
	v_cmp_lt_u32_e64 s[8:9], 1, v51
	s_and_b64 s[0:1], s[8:9], exec
	s_or_saveexec_b64 s[8:9], s[12:13]
	s_waitcnt lgkmcnt(0)
	v_add_f32_e32 v7, 0, v38
	s_or_b64 s[12:13], vcc, s[6:7]
	v_cndmask_b32_e64 v8, v7, 0, s[12:13]
	v_mov_b32_e32 v5, v8
	s_xor_b64 exec, exec, s[8:9]
	s_andn2_b64 s[0:1], s[0:1], exec
	s_and_b64 s[12:13], s[6:7], exec
	v_mov_b32_e32 v5, 0
	s_or_b64 s[0:1], s[0:1], s[12:13]
	s_or_b64 exec, exec, s[8:9]
	s_and_saveexec_b64 s[8:9], s[0:1]
	v_add_f32_e32 v5, v39, v8
	s_or_b64 exec, exec, s[8:9]
	ds_read_b32 v8, v2 offset:512
	s_mov_b64 s[0:1], 0
	v_cmp_eq_u32_e64 s[8:9], 3, v51
	s_and_saveexec_b64 s[12:13], s[4:5]
	s_xor_b64 s[4:5], exec, s[12:13]
	s_cbranch_execnz .LBB0_621
	s_andn2_saveexec_b64 s[8:9], s[4:5]
	s_cbranch_execnz .LBB0_622
